# grid sync: per-XCC arrival counters + single top counter, one L2 writeback per XCC (census via XCC_ID)
# speedup vs baseline: 1.0398x; 1.0107x over previous
; __device__ __forceinline__ int otid(int wv) { int l; asm volatile("v_mbcnt_lo_u32_b32 %0, -1, 0\n\tv_mbcnt_hi_u32_b32 %0, -1, %0" : "=v"(l)); return wv * 64 + l; }
; __device__ __forceinline__ KArgs kargs() { auto p = __builtin_amdgcn_kernarg_segment_ptr(); asm volatile("" : "+s"(p)); return (KArgs)p; }
;     __device__ bool next(int i, Unit& u) const {
;         const long L = (long)i * G + c; if (L >= nwg) return false;
;         int wgid = (int)L; { const int q = nwg / NXCD, r = nwg % NXCD, xcd = wgid % NXCD, off = wgid / NXCD; wgid = (xcd < r ? xcd * (q + 1) : r * (q + 1) + (xcd - r) * q) + off; }
;         const int nig = WGM * nN, gid = wgid / nig, fm = gid * WGM, gsz = (nM - fm) < WGM ? (nM - fm) : WGM;
;         u.pm = fm + ((wgid % nig) % gsz); u.pn = (wgid % nig) / gsz; return true;
; __global__ void __launch_bounds__(512, 2) mega(Args a_unused) {
;     extern __shared__ __attribute__((aligned(16))) unsigned char lds[];
;     const int wv = __builtin_amdgcn_readfirstlane(threadIdx.x >> 6);
;     const int lo = kargs()->lo;
; #pragma unroll 1
;     for (int ph = lo; ph < kargs()->hi; ++ph) {
;         KArgs ap = kargs();
;         const int G = gridDim.x, bx = blockIdx.x;
;         const int vcu = (G % 8 == 0) ? (bx % 8) * (G / 8) + bx / 8 : bx;
;         unsigned char* ws = ap->ws;
;         bf16_t* H = (bf16_t*)(ws + WS_H);
;         unsigned char* BIG = ws + WS_BIG;
;         float* MBUF = (float*)(ws + WS_MBUF);
;         const int tid = otid(wv), wid = __builtin_amdgcn_readfirstlane(tid >> 6), lane = tid & 63;
;         const int gw = vcu * 8 + wid, NGW = G * 8;
_Z4mega4Args:
	s_mov_b32 s100, 0
	s_mov_b32 s101, 0
	v_and_b32_e32 v1, 0x3ff, v0
	s_mov_b64 s[82:83], s[0:1]
	v_readfirstlane_b32 s3, v1
	s_andn2_b32 s3, s3, 63
	s_load_dword s88, s[0:1], 0xa8
	s_add_u32 s0, s82, 0xb8
	s_addc_u32 s1, s83, 0
	s_ashr_i32 s89, s2, 31
	v_writelane_b32 v254, s0, 0
	s_mov_b32 s80, s2
	v_and_b32_e32 v0, 0x3fffffff, v0
	v_writelane_b32 v254, s1, 1
	s_lshr_b32 s0, s89, 29
	s_add_i32 s0, s2, s0
	s_ashr_i32 s9, s0, 3
	s_and_b32 s0, s0, -8
	s_sub_i32 s10, s2, s0
	s_cmpk_lt_i32 s2, 0xb00
	s_cselect_b64 s[0:1], -1, 0
	v_writelane_b32 v254, s0, 2
	s_cmpk_lt_i32 s2, 0x200
	s_movk_i32 s73, 0xc0
	v_writelane_b32 v254, s1, 3
	s_cselect_b64 s[0:1], -1, 0
	v_writelane_b32 v254, s0, 4
	s_movk_i32 s71, 0x60
	s_mov_b32 s67, 0x10000
	v_writelane_b32 v254, s1, 5
	s_lshl_b32 s0, s10, 6
	s_cmpk_lt_i32 s2, 0x600
	s_cselect_b64 s[4:5], -1, 0
	v_writelane_b32 v254, s4, 6
	s_cmpk_lt_i32 s2, 0x400
	s_mul_i32 s2, s10, 0x41
	v_writelane_b32 v254, s5, 7
	s_cselect_b64 s[4:5], -1, 0
	v_writelane_b32 v254, s4, 8
	s_lshl_b32 s1, s10, 7
	s_cmp_lt_i32 s10, 0
	v_writelane_b32 v254, s5, 9
	s_movk_i32 s5, 0x161
	s_cselect_b32 s5, s5, 0x160
	s_mul_i32 s4, s10, 0x81
	s_mul_i32 s5, s10, s5
	s_cselect_b32 s2, s2, s0
	s_movk_i32 s0, 0xc1
	s_cselect_b32 s6, s0, 0xc0
	s_cselect_b32 s4, s4, s1
	s_add_i32 s5, s5, s9
	s_mul_hi_i32 s0, s5, 0x2e8ba2e9
	s_lshr_b32 s1, s0, 31
	s_ashr_i32 s0, s0, 5
	s_add_i32 s0, s0, s1
	s_mul_i32 s1, s0, 0xb0
	s_sub_i32 s1, s5, s1
	s_lshl_b32 s7, s0, 2
	s_bfe_u32 s0, s1, 0x2001d
	s_add_i32 s5, s1, s0
	s_sext_i32_i16 s8, s5
	s_and_b32 s5, s5, 0xfffc
	s_sub_i32 s1, s1, s5
	s_sext_i32_i16 s1, s1
	s_lshr_b32 s0, s8, 2
	s_add_i32 s12, s7, s1
	s_ashr_i32 s1, s8, 2
	v_writelane_b32 v254, s1, 10
	s_bfe_i64 s[0:1], s[0:1], 0x100000
	s_lshl_b64 s[0:1], s[0:1], 20
	v_writelane_b32 v254, s0, 11
	s_ashr_i32 s13, s12, 31
	v_mov_b32_e32 v211, 0
	v_writelane_b32 v254, s1, 12
	s_add_i32 s0, s2, s9
	s_ashr_i32 s1, s0, 31
	s_lshr_b32 s1, s1, 27
	s_add_i32 s1, s0, s1
	s_ashr_i32 s2, s1, 5
	s_and_b32 s1, s1, 0xffe0
	s_sub_i32 s1, s0, s1
	s_bfe_i32 s0, s1, 0x80000
	s_bfe_u32 s0, s0, 0x2000d
	s_add_i32 s5, s1, s0
	s_bfe_i32 s0, s5, 0x80000
	s_and_b32 s5, s5, 0xfc
	s_sub_i32 s1, s1, s5
	s_lshl_b32 s2, s2, 2
	s_sext_i32_i8 s1, s1
	s_sext_i32_i16 s7, s0
	s_add_i32 s1, s2, s1
	s_lshr_b32 s0, s7, 2
	v_writelane_b32 v254, s1, 13
	s_ashr_i32 s1, s7, 2
	v_writelane_b32 v254, s1, 14
	s_bfe_i64 s[0:1], s[0:1], 0x100000
	v_writelane_b32 v254, s0, 15
	s_mov_b32 s75, 0x14000
	s_movk_i32 s69, 0x4000
	v_writelane_b32 v254, s1, 16
	s_mul_i32 s0, s10, s6
	s_add_i32 s0, s0, s9
	s_mul_hi_i32 s1, s0, 0x2aaaaaab
	s_lshr_b32 s2, s1, 31
	s_ashr_i32 s1, s1, 4
	s_add_i32 s1, s1, s2
	s_mul_i32 s2, s1, 0x60
	s_sub_i32 s2, s0, s2
	s_bfe_i32 s0, s2, 0x80000
	s_bfe_u32 s0, s0, 0x2000d
	s_add_i32 s5, s2, s0
	s_bfe_i32 s0, s5, 0x80000
	s_and_b32 s5, s5, 0xfc
	s_sub_i32 s2, s2, s5
	s_lshl_b32 s1, s1, 2
	s_sext_i32_i16 s6, s0
	s_sext_i32_i8 s2, s2
	v_writelane_b32 v254, s10, 17
	s_lshr_b32 s0, s6, 2
	s_add_i32 s10, s1, s2
	s_ashr_i32 s1, s6, 2
	v_writelane_b32 v254, s1, 18
	s_bfe_i64 s[0:1], s[0:1], 0x100000
	s_lshl_b64 s[0:1], s[0:1], 20
	v_writelane_b32 v254, s0, 19
	v_cmp_eq_u32_e64 s[6:7], 0, v0
	s_ashr_i32 s11, s10, 31
	v_writelane_b32 v254, s1, 20
	s_add_i32 s0, s4, s9
	s_ashr_i32 s1, s0, 31
	s_lshr_b32 s1, s1, 26
	s_add_i32 s1, s0, s1
	s_ashr_i32 s2, s1, 6
	s_and_b32 s1, s1, 0xffc0
	s_sub_i32 s1, s0, s1
	s_bfe_i32 s0, s1, 0x80000
	s_bfe_u32 s0, s0, 0x2000d
	s_add_i32 s4, s1, s0
	s_bfe_i32 s0, s4, 0x80000
	s_and_b32 s4, s4, 0xfc
	s_sub_i32 s1, s1, s4
	s_lshl_b32 s2, s2, 2
	s_sext_i32_i16 s5, s0
; __device__ __forceinline__ int otid(int wv) { int l; asm volatile("v_mbcnt_lo_u32_b32 %0, -1, 0\n\tv_mbcnt_hi_u32_b32 %0, -1, %0" : "=v"(l)); return wv * 64 + l; }
; __device__ __forceinline__ KArgs kargs() { auto p = __builtin_amdgcn_kernarg_segment_ptr(); asm volatile("" : "+s"(p)); return (KArgs)p; }
; __global__ void __launch_bounds__(512, 2) mega(Args a_unused) {
;     extern __shared__ __attribute__((aligned(16))) unsigned char lds[];
;     const int wv = __builtin_amdgcn_readfirstlane(threadIdx.x >> 6);
;     const int lo = kargs()->lo;
; #pragma unroll 1
;     for (int ph = lo; ph < kargs()->hi; ++ph) {
;         KArgs ap = kargs();
;         const int G = gridDim.x, bx = blockIdx.x;
;         const int vcu = (G % 8 == 0) ? (bx % 8) * (G / 8) + bx / 8 : bx;
;         unsigned char* ws = ap->ws;
;         bf16_t* H = (bf16_t*)(ws + WS_H);
;         unsigned char* BIG = ws + WS_BIG;
;         float* MBUF = (float*)(ws + WS_MBUF);
;         const int tid = otid(wv), wid = __builtin_amdgcn_readfirstlane(tid >> 6), lane = tid & 63;
;         const int gw = vcu * 8 + wid, NGW = G * 8;
	s_sext_i32_i8 s1, s1
	v_writelane_b32 v254, s9, 21
	s_lshr_b32 s0, s5, 2
	s_add_i32 s4, s2, s1
	s_ashr_i32 s1, s5, 2
	v_writelane_b32 v254, s1, 22
	s_bfe_i64 s[0:1], s[0:1], 0x100000
	s_lshl_b64 s[0:1], s[0:1], 20
	v_writelane_b32 v254, s0, 23
	s_mov_b32 s2, s12
	s_ashr_i32 s5, s4, 31
	v_writelane_b32 v254, s1, 24
	s_add_i32 s1, 0, 0x1f808
	v_writelane_b32 v254, s1, 25
	s_add_i32 s1, 0, 0x1f810
	v_writelane_b32 v254, s1, 26
	s_add_i32 s1, 0, 0x1f818
	v_writelane_b32 v254, s1, 27
	s_add_i32 s1, 0, 0x1f820
	v_writelane_b32 v254, s1, 28
	s_add_i32 s1, 0, 0x1f828
	v_writelane_b32 v254, s1, 29
	s_add_i32 s1, 0, 0x1f830
	v_writelane_b32 v254, s1, 30
	s_add_i32 s1, 0, 0x1f838
	v_writelane_b32 v254, s1, 31
	s_add_i32 s1, 0, 0x1f840
	v_writelane_b32 v254, s1, 32
	s_add_i32 s1, 0, 0x1f848
	v_writelane_b32 v254, s1, 33
	s_add_i32 s1, 0, 0x1f850
	v_writelane_b32 v254, s1, 34
	s_add_i32 s1, 0, 0x1f858
	v_writelane_b32 v254, s1, 35
	s_add_i32 s1, 0, 0x1f860
	v_writelane_b32 v254, s1, 36
	s_add_i32 s1, 0, 0x1f868
	v_writelane_b32 v254, s1, 37
	s_add_i32 s1, 0, 0x1f870
	v_writelane_b32 v254, s1, 38
	s_add_i32 s1, 0, 0x1f878
	v_writelane_b32 v254, s1, 39
	s_add_i32 s1, 0, 0x1f880
	v_writelane_b32 v254, s1, 40
	s_add_i32 s1, 0, 0x1f888
	v_writelane_b32 v254, s1, 41
	s_add_i32 s1, 0, 0x1f890
	v_writelane_b32 v254, s1, 42
	s_add_i32 s1, 0, 0x1f898
	v_writelane_b32 v254, s1, 43
	s_add_i32 s1, 0, 0x1f8a0
	v_writelane_b32 v254, s1, 44
	s_add_i32 s1, 0, 0x1f8a8
	v_writelane_b32 v254, s1, 45
	s_add_i32 s1, 0, 0x1f8b0
	v_writelane_b32 v254, s1, 46
	s_add_i32 s1, 0, 0x1f8b8
	v_writelane_b32 v254, s1, 47
	s_add_i32 s1, 0, 0x1f8c0
	v_writelane_b32 v254, s1, 48
	s_add_i32 s1, 0, 0x1f8c8
	v_writelane_b32 v254, s1, 49
	s_add_i32 s1, 0, 0x1f8d0
	v_writelane_b32 v254, s1, 50
	s_add_i32 s1, 0, 0x1f8d8
	v_writelane_b32 v254, s1, 51
	s_add_i32 s1, 0, 0x1f8e0
	v_writelane_b32 v254, s1, 52
	s_add_i32 s1, 0, 0x1f8e8
	v_writelane_b32 v254, s1, 53
	s_add_i32 s1, 0, 0x1f8f0
	v_writelane_b32 v254, s1, 54
	s_add_i32 s1, 0, 0x1f8f8
	v_writelane_b32 v254, s1, 55
	v_writelane_b32 v254, s6, 56
	s_mov_b32 s90, 0x18000
	s_mov_b32 s91, 0x8000
	v_writelane_b32 v254, s7, 57
	v_writelane_b32 v254, s2, 58
	s_lshl_b64 s[6:7], s[12:13], 20
	s_mov_b32 s33, 0x1c000
	v_writelane_b32 v254, s3, 59
	v_writelane_b32 v254, s6, 60
	s_mov_b32 s2, s10
	s_mov_b32 s76, 0xc000
	v_writelane_b32 v254, s7, 61
	s_lshl_b64 s[6:7], s[10:11], 20
	v_writelane_b32 v254, s2, 62
	v_writelane_b32 v255, s6, 0
	s_movk_i32 s86, 0x2c00
	v_writelane_b32 v254, s3, 63
	v_writelane_b32 v255, s7, 1
	s_mov_b32 s2, s4
	v_writelane_b32 v255, s2, 2
	s_lshl_b64 s[4:5], s[4:5], 20
	s_movk_i32 s92, 0x1000
	v_writelane_b32 v255, s3, 3
	v_writelane_b32 v255, s4, 4
	v_mov_b32_e32 v244, 0x358637bd
	s_mov_b32 s81, 0xf800000
	v_writelane_b32 v255, s5, 5
	v_writelane_b32 v255, s82, 6
	v_mov_b32_e32 v245, 0x260
	s_movk_i32 s0, 0x3000
	v_writelane_b32 v255, s83, 7
	v_writelane_b32 v255, s80, 8
	s_mov_b32 s53, 0x41000000
	v_mov_b32_e32 v246, 1
	v_mov_b32_e32 v247, 0x3db504f3
	v_mov_b32_e32 v248, 0x7f800000
	s_mov_b32 s50, 0x20000
	s_mov_b32 s51, 0x28000
	s_mov_b32 s78, 0x30000
	s_mov_b32 s39, 0
	s_mov_b64 s[46:47], 0x80
	s_mov_b64 s[48:49], 0x100
	s_mov_b64 s[94:95], 0x1000
	s_mov_b64 s[96:97], 0x1800
	s_mov_b64 s[54:55], 0x1b982000
	s_mov_b64 s[56:57], 0x1b982100
	s_mov_b64 s[58:59], 0x1b8c2000
	s_mov_b64 s[60:61], 0x1b8c2100
	s_mov_b64 s[62:63], 0x8000
	s_mov_b32 s64, 0x3e6d3388
	s_mov_b32 s66, 0x3f07dc22
	s_mov_b32 s68, 0x3f35f0e3
	s_mov_b32 s70, 0xbe11a98e
	s_mov_b32 s72, 0x3e027906
	s_mov_b32 s74, 0xbf38aa3b
	v_writelane_b32 v255, s89, 9
	s_branch .LBB0_5

; __device__ __forceinline__ KArgs kargs() { auto p = __builtin_amdgcn_kernarg_segment_ptr(); asm volatile("" : "+s"(p)); return (KArgs)p; }
; __global__ void __launch_bounds__(512, 2) mega(Args a_unused) {
;     ...
;         if (ph + 1 < kargs()->hi) { if (kargs()->coop) cg::this_grid().sync(); }
.LBB0_455:
	s_cmp_lt_u32 s88, 2
	s_cbranch_scc1 .Lgs_pre_slow
	s_cmp_ge_u32 s88, 4
	s_cbranch_scc1 .Lgs_hier
	s_load_dwordx2 s[6:7], s[82:83], 0xa0
	s_load_dword s1, s[82:83], 0xb8
	buffer_wbl2 sc1
	s_and_b32 s8, s80, 7
	s_lshl_b32 s8, s8, 8
	s_add_i32 s100, s100, 1
	s_mov_b64 s[12:13], exec
	s_mov_b32 exec_lo, 0x1ffff
	s_mov_b32 exec_hi, 0
	v_mbcnt_lo_u32_b32 v0, -1, 0
	s_waitcnt lgkmcnt(0)
	s_add_i32 s1, s1, 7
	v_sub_u32_e32 v2, s1, v0
	v_lshrrev_b32_e32 v2, 3, v2
	v_mul_lo_u32 v2, v2, s100
	v_lshlrev_b32_e32 v0, 8, v0
	s_cmp_eq_u32 s88, 3
	s_cbranch_scc0 .Lgs_noinit
	s_cmp_eq_u32 s80, 0
	s_cbranch_scc0 .Lgs_noinit
	global_store_dword v0, v211, s[6:7] sc0 sc1
.Lgs_noinit:
	s_mov_b64 exec, s[12:13]
	s_cmp_eq_u32 s88, 2
	s_cbranch_scc0 .Lgs_nocensus
	s_getreg_b32 s9, hwreg(HW_REG_XCC_ID, 0, 4)
	s_lshl_b32 s9, s9, 2
	s_add_u32 s10, s6, 0x337ff800
	s_addc_u32 s11, s7, 0
	s_add_u32 s10, s10, s9
	s_addc_u32 s11, s11, 0
	v_mov_b32_e32 v1, 1
	global_atomic_add v211, v1, s[10:11]
.Lgs_nocensus:
	s_add_u32 s6, s6, 0x337ff000
	s_addc_u32 s7, s7, 0
	s_add_u32 s8, s6, s8
	s_addc_u32 s9, s7, 0
	v_mov_b32_e32 v1, 1
	s_waitcnt vmcnt(0)
	global_atomic_add v211, v1, s[8:9]
	s_mov_b32 exec_lo, 0xff
	s_mov_b32 exec_hi, 0

; __device__ __forceinline__ KArgs kargs() { auto p = __builtin_amdgcn_kernarg_segment_ptr(); asm volatile("" : "+s"(p)); return (KArgs)p; }
; __global__ void __launch_bounds__(512, 2) mega(Args a_unused) {
;     ...
;         if (ph + 1 < kargs()->hi) { if (kargs()->coop) cg::this_grid().sync(); }
.Lgs_hier:
	s_load_dwordx2 s[6:7], s[82:83], 0xa0
	s_getreg_b32 s11, hwreg(HW_REG_XCC_ID, 0, 4)
	s_add_i32 s101, s101, 1
	s_cmp_lg_u32 s88, 4
	s_cbranch_scc1 .Lgs_have_census
	s_waitcnt lgkmcnt(0)
	s_add_u32 s8, s6, 0x337ff800
	s_addc_u32 s9, s7, 0
	s_mov_b64 s[12:13], exec
	s_mov_b32 exec_lo, 0xffff
	s_mov_b32 exec_hi, 0
	v_mbcnt_lo_u32_b32 v0, -1, 0
	v_lshlrev_b32_e32 v1, 2, v0
	global_load_dword v1, v1, s[8:9] sc1
	s_waitcnt vmcnt(0)
	v_cmp_ne_u32_e32 vcc, 0, v1
	s_bcnt1_i32_b64 s10, vcc
	s_nop 3
	v_readlane_b32 s1, v1, s11
	s_mov_b64 exec, s[12:13]
	s_nop 0
	v_writelane_b32 v255, s1, 61
	v_writelane_b32 v255, s10, 62
.Lgs_have_census:
	s_nop 0
	v_readlane_b32 s1, v255, 61
	v_readlane_b32 s10, v255, 62
	s_waitcnt lgkmcnt(0)
	s_add_i32 s11, s11, 1
	s_lshl_b32 s11, s11, 8
	s_add_u32 s8, s6, s11
	s_addc_u32 s9, s7, 0
	v_mov_b32_e32 v1, 1
	global_atomic_add v0, v211, v1, s[8:9] sc0
	s_mul_i32 s1, s1, s101
	s_mul_i32 s10, s10, s101
	s_waitcnt vmcnt(0)
	v_readfirstlane_b32 s11, v0
	s_add_i32 s11, s11, 1
	s_cmp_lg_u32 s11, s1
	s_cbranch_scc1 .Lgs_hpoll
	buffer_wbl2 sc1
	s_waitcnt vmcnt(0)
	global_atomic_add v211, v1, s[6:7]
.Lgs_hpoll:
	global_load_dword v0, v211, s[6:7] sc1
	s_waitcnt vmcnt(0)
	v_readfirstlane_b32 s11, v0
	s_cmp_ge_u32 s11, s10
	s_cbranch_scc1 .Lgs_join
	s_sleep 1
	s_branch .Lgs_hpoll
.Lgs_pre_slow:
	s_cmp_lg_u32 s80, 0
	s_cbranch_scc1 .Lgs_slow
	s_load_dwordx2 s[6:7], s[82:83], 0xa0
	s_mov_b64 s[12:13], exec
	s_mov_b32 exec_lo, 0xffff
	s_mov_b32 exec_hi, 0
	v_mbcnt_lo_u32_b32 v0, -1, 0
	v_lshlrev_b32_e32 v1, 2, v0
	v_lshlrev_b32_e32 v0, 8, v0
	s_waitcnt lgkmcnt(0)
	s_add_u32 s8, s6, 0x337ff800
	s_addc_u32 s9, s7, 0
	s_add_u32 s6, s6, 0x337ff000
	s_addc_u32 s7, s7, 0
	global_store_dword v1, v211, s[8:9] sc0 sc1
	s_mov_b32 exec_lo, 0xff
	global_store_dword v0, v211, s[6:7] sc0 sc1
	s_waitcnt vmcnt(0)
	s_mov_b64 exec, s[12:13]

; __global__ void __launch_bounds__(512, 2) mega(Args a_unused) {
	.amdhsa_kernel _Z4mega4Args
		.amdhsa_group_segment_fixed_size 0
		.amdhsa_private_segment_fixed_size 0
		.amdhsa_kernarg_size 440
		.amdhsa_user_sgpr_count 2
		.amdhsa_user_sgpr_dispatch_ptr 0
		.amdhsa_user_sgpr_queue_ptr 0
		.amdhsa_user_sgpr_kernarg_segment_ptr 1
		.amdhsa_user_sgpr_dispatch_id 0
		.amdhsa_user_sgpr_kernarg_preload_length 0
		.amdhsa_user_sgpr_kernarg_preload_offset 0
		.amdhsa_user_sgpr_private_segment_size 0
		.amdhsa_uses_dynamic_stack 0
		.amdhsa_enable_private_segment 0
		.amdhsa_system_sgpr_workgroup_id_x 1
		.amdhsa_system_sgpr_workgroup_id_y 0
		.amdhsa_system_sgpr_workgroup_id_z 0
		.amdhsa_system_sgpr_workgroup_info 0
		.amdhsa_system_vgpr_workitem_id 2
		.amdhsa_next_free_vgpr 256
		.amdhsa_next_free_sgpr 102
		.amdhsa_accum_offset 256
		.amdhsa_reserve_vcc 1
		.amdhsa_float_round_mode_32 0
		.amdhsa_float_round_mode_16_64 0
		.amdhsa_float_denorm_mode_32 3
		.amdhsa_float_denorm_mode_16_64 3
		.amdhsa_dx10_clamp 1
		.amdhsa_ieee_mode 1
		.amdhsa_fp16_overflow 0
		.amdhsa_tg_split 0
		.amdhsa_exception_fp_ieee_invalid_op 0
		.amdhsa_exception_fp_denorm_src 0
		.amdhsa_exception_fp_ieee_div_zero 0
		.amdhsa_exception_fp_ieee_overflow 0
		.amdhsa_exception_fp_ieee_underflow 0
		.amdhsa_exception_fp_ieee_inexact 0
		.amdhsa_exception_int_div_zero 0
	.end_amdhsa_kernel

; __global__ void __launch_bounds__(512, 2) mega(Args a_unused) {
amdhsa.kernels:
  - .agpr_count:     0
    .args:
      - .offset:         0
        .size:           184
        .value_kind:     by_value
      - .offset:         184
        .size:           4
        .value_kind:     hidden_block_count_x
      - .offset:         188
        .size:           4
        .value_kind:     hidden_block_count_y
      - .offset:         192
        .size:           4
        .value_kind:     hidden_block_count_z
      - .offset:         196
        .size:           2
        .value_kind:     hidden_group_size_x
      - .offset:         198
        .size:           2
        .value_kind:     hidden_group_size_y
      - .offset:         200
        .size:           2
        .value_kind:     hidden_group_size_z
      - .offset:         202
        .size:           2
        .value_kind:     hidden_remainder_x
      - .offset:         204
        .size:           2
        .value_kind:     hidden_remainder_y
      - .offset:         206
        .size:           2
        .value_kind:     hidden_remainder_z
      - .offset:         224
        .size:           8
        .value_kind:     hidden_global_offset_x
      - .offset:         232
        .size:           8
        .value_kind:     hidden_global_offset_y
      - .offset:         240
        .size:           8
        .value_kind:     hidden_global_offset_z
      - .offset:         248
        .size:           2
        .value_kind:     hidden_grid_dims
      - .offset:         272
        .size:           8
        .value_kind:     hidden_multigrid_sync_arg
      - .offset:         304
        .size:           4
        .value_kind:     hidden_dynamic_lds_size
    .group_segment_fixed_size: 0
    .kernarg_segment_align: 8
    .kernarg_segment_size: 440
    .language:       OpenCL C
    .language_version:
      - 2
      - 0
    .max_flat_workgroup_size: 512
    .name:           _Z4mega4Args
    .private_segment_fixed_size: 0
    .sgpr_count:     108
    .sgpr_spill_count: 134
    .symbol:         _Z4mega4Args.kd
    .uniform_work_group_size: 1
    .uses_dynamic_stack: false
    .vgpr_count:     256
    .vgpr_spill_count: 0
    .wavefront_size: 64
